# v26 + P0a GEMV: silu(c) staging as 34 loads + one wait instead of 34 serialized load/wait/compute iterations
# speedup vs baseline: 1.0142x; 1.0077x over previous
; #define LAS __attribute__((address_space(3)))
; __device__ __forceinline__ float silu_f(float x) { return x * __builtin_amdgcn_rcpf(1.f + __expf(-x)); }
; __device__ __forceinline__ void phase0a(const Params& P, LAS unsigned char* lds, int tid, int lane, int wave, int bid, int G) {
;     ...
;     for (int it = bid; it < 96; it += G) {
;         LAS float* sc = (LAS float*)lds;
;         LAS float* red = (LAS float*)(lds + 72 * 1024);
;         for (int i = tid; i < 17 * 1024; i += 512) { const float c = i < 16 * 1024 ? P.cp[i] : P.csm[i - 16 * 1024]; sc[i] = silu_f(c); }
;         __syncthreads();
.LBB0_9:
	s_mov_b64 s[0:1], 0x1000
	v_mov_b64_e32 v[46:47], v[4:5]
	global_load_dword v100, v[46:47], off
	global_load_dword v101, v[46:47], off offset:2048
	v_lshl_add_u64 v[46:47], v[46:47], 0, s[0:1]
	global_load_dword v102, v[46:47], off
	global_load_dword v103, v[46:47], off offset:2048
	v_lshl_add_u64 v[46:47], v[46:47], 0, s[0:1]
	global_load_dword v104, v[46:47], off
	global_load_dword v105, v[46:47], off offset:2048
	v_lshl_add_u64 v[46:47], v[46:47], 0, s[0:1]
	global_load_dword v106, v[46:47], off
	global_load_dword v107, v[46:47], off offset:2048
	v_lshl_add_u64 v[46:47], v[46:47], 0, s[0:1]
	global_load_dword v108, v[46:47], off
	global_load_dword v109, v[46:47], off offset:2048
	v_lshl_add_u64 v[46:47], v[46:47], 0, s[0:1]
	global_load_dword v110, v[46:47], off
	global_load_dword v111, v[46:47], off offset:2048
	v_lshl_add_u64 v[46:47], v[46:47], 0, s[0:1]
	global_load_dword v112, v[46:47], off
	global_load_dword v113, v[46:47], off offset:2048
	v_lshl_add_u64 v[46:47], v[46:47], 0, s[0:1]
	global_load_dword v114, v[46:47], off
	global_load_dword v115, v[46:47], off offset:2048
	v_lshl_add_u64 v[46:47], v[46:47], 0, s[0:1]
	global_load_dword v116, v[46:47], off
	global_load_dword v117, v[46:47], off offset:2048
	v_lshl_add_u64 v[46:47], v[46:47], 0, s[0:1]
	global_load_dword v118, v[46:47], off
	global_load_dword v119, v[46:47], off offset:2048
	v_lshl_add_u64 v[46:47], v[46:47], 0, s[0:1]
	global_load_dword v120, v[46:47], off
	global_load_dword v121, v[46:47], off offset:2048
	v_lshl_add_u64 v[46:47], v[46:47], 0, s[0:1]
	global_load_dword v122, v[46:47], off
	global_load_dword v123, v[46:47], off offset:2048
	v_lshl_add_u64 v[46:47], v[46:47], 0, s[0:1]
	global_load_dword v124, v[46:47], off
	global_load_dword v125, v[46:47], off offset:2048
	v_lshl_add_u64 v[46:47], v[46:47], 0, s[0:1]
	global_load_dword v126, v[46:47], off
	global_load_dword v127, v[46:47], off offset:2048
	v_lshl_add_u64 v[46:47], v[46:47], 0, s[0:1]
	global_load_dword v128, v[46:47], off
	global_load_dword v129, v[46:47], off offset:2048
	v_lshl_add_u64 v[46:47], v[46:47], 0, s[0:1]
	global_load_dword v130, v[46:47], off
	global_load_dword v131, v[46:47], off offset:2048
	s_mov_b64 s[0:1], 0x10000
	v_lshl_add_u64 v[48:49], v[2:3], 0, s[0:1]
	global_load_dword v132, v[48:49], off
	global_load_dword v133, v[48:49], off offset:2048
	v_add_u32_e32 v50, 0x10000, v40
	s_waitcnt vmcnt(0)
; __device__ __forceinline__ float silu_f(float x) { return x * __builtin_amdgcn_rcpf(1.f + __expf(-x)); }
; __device__ __forceinline__ void phase0a(const Params& P, LAS unsigned char* lds, int tid, int lane, int wave, int bid, int G) {
;     ...
;         for (int i = tid; i < 17 * 1024; i += 512) { const float c = i < 16 * 1024 ? P.cp[i] : P.csm[i - 16 * 1024]; sc[i] = silu_f(c); }
;         __syncthreads();
;         const int cl = tid & 31, kg = tid >> 5, col = it * 32 + cl;
;         float acc[17];
; #pragma unroll
;         for (int s = 0; s < 17; ++s) acc[s] = 0.f;
	v_mul_f32_e32 v51, 0xbfb8aa3b, v100
	v_mul_f32_e32 v52, 0xbfb8aa3b, v101
	v_exp_f32_e32 v51, v51
	v_exp_f32_e32 v52, v52
	s_nop 0
	v_add_f32_e32 v51, 1.0, v51
	v_add_f32_e32 v52, 1.0, v52
	v_rcp_f32_e32 v51, v51
	v_rcp_f32_e32 v52, v52
	s_nop 0
	v_mul_f32_e32 v51, v100, v51
	v_mul_f32_e32 v52, v101, v52
	ds_write_b32 v40, v51
	ds_write_b32 v40, v52 offset:2048
	v_mul_f32_e32 v51, 0xbfb8aa3b, v102
	v_mul_f32_e32 v52, 0xbfb8aa3b, v103
	v_exp_f32_e32 v51, v51
	v_exp_f32_e32 v52, v52
	s_nop 0
	v_add_f32_e32 v51, 1.0, v51
	v_add_f32_e32 v52, 1.0, v52
	v_rcp_f32_e32 v51, v51
	v_rcp_f32_e32 v52, v52
	s_nop 0
	v_mul_f32_e32 v51, v102, v51
	v_mul_f32_e32 v52, v103, v52
	ds_write_b32 v40, v51 offset:4096
	ds_write_b32 v40, v52 offset:6144
	v_mul_f32_e32 v51, 0xbfb8aa3b, v104
	v_mul_f32_e32 v52, 0xbfb8aa3b, v105
	v_exp_f32_e32 v51, v51
	v_exp_f32_e32 v52, v52
	s_nop 0
	v_add_f32_e32 v51, 1.0, v51
	v_add_f32_e32 v52, 1.0, v52
	v_rcp_f32_e32 v51, v51
	v_rcp_f32_e32 v52, v52
	s_nop 0
	v_mul_f32_e32 v51, v104, v51
	v_mul_f32_e32 v52, v105, v52
	ds_write_b32 v40, v51 offset:8192
	ds_write_b32 v40, v52 offset:10240
	v_mul_f32_e32 v51, 0xbfb8aa3b, v106
	v_mul_f32_e32 v52, 0xbfb8aa3b, v107
	v_exp_f32_e32 v51, v51
	v_exp_f32_e32 v52, v52
	s_nop 0
	v_add_f32_e32 v51, 1.0, v51
	v_add_f32_e32 v52, 1.0, v52
	v_rcp_f32_e32 v51, v51
	v_rcp_f32_e32 v52, v52
	s_nop 0
	v_mul_f32_e32 v51, v106, v51
	v_mul_f32_e32 v52, v107, v52
	ds_write_b32 v40, v51 offset:12288
	ds_write_b32 v40, v52 offset:14336
	v_mul_f32_e32 v51, 0xbfb8aa3b, v108
	v_mul_f32_e32 v52, 0xbfb8aa3b, v109
	v_exp_f32_e32 v51, v51
	v_exp_f32_e32 v52, v52
	s_nop 0
	v_add_f32_e32 v51, 1.0, v51
	v_add_f32_e32 v52, 1.0, v52
	v_rcp_f32_e32 v51, v51
	v_rcp_f32_e32 v52, v52
	s_nop 0
	v_mul_f32_e32 v51, v108, v51
	v_mul_f32_e32 v52, v109, v52
	ds_write_b32 v40, v51 offset:16384
	ds_write_b32 v40, v52 offset:18432
	v_mul_f32_e32 v51, 0xbfb8aa3b, v110
	v_mul_f32_e32 v52, 0xbfb8aa3b, v111
	v_exp_f32_e32 v51, v51
	v_exp_f32_e32 v52, v52
	s_nop 0
	v_add_f32_e32 v51, 1.0, v51
	v_add_f32_e32 v52, 1.0, v52
	v_rcp_f32_e32 v51, v51
	v_rcp_f32_e32 v52, v52
	s_nop 0
	v_mul_f32_e32 v51, v110, v51
	v_mul_f32_e32 v52, v111, v52
	ds_write_b32 v40, v51 offset:20480
	ds_write_b32 v40, v52 offset:22528
	v_mul_f32_e32 v51, 0xbfb8aa3b, v112
	v_mul_f32_e32 v52, 0xbfb8aa3b, v113
	v_exp_f32_e32 v51, v51
	v_exp_f32_e32 v52, v52
	s_nop 0
	v_add_f32_e32 v51, 1.0, v51
	v_add_f32_e32 v52, 1.0, v52
	v_rcp_f32_e32 v51, v51
	v_rcp_f32_e32 v52, v52
	s_nop 0
	v_mul_f32_e32 v51, v112, v51
	v_mul_f32_e32 v52, v113, v52
	ds_write_b32 v40, v51 offset:24576
	ds_write_b32 v40, v52 offset:26624
	v_mul_f32_e32 v51, 0xbfb8aa3b, v114
	v_mul_f32_e32 v52, 0xbfb8aa3b, v115
	v_exp_f32_e32 v51, v51
	v_exp_f32_e32 v52, v52
	s_nop 0
	v_add_f32_e32 v51, 1.0, v51
	v_add_f32_e32 v52, 1.0, v52
	v_rcp_f32_e32 v51, v51
	v_rcp_f32_e32 v52, v52
	s_nop 0
	v_mul_f32_e32 v51, v114, v51
	v_mul_f32_e32 v52, v115, v52
	ds_write_b32 v40, v51 offset:28672
	ds_write_b32 v40, v52 offset:30720
	v_mul_f32_e32 v51, 0xbfb8aa3b, v116
	v_mul_f32_e32 v52, 0xbfb8aa3b, v117
	v_exp_f32_e32 v51, v51
	v_exp_f32_e32 v52, v52
	s_nop 0
	v_add_f32_e32 v51, 1.0, v51
	v_add_f32_e32 v52, 1.0, v52
	v_rcp_f32_e32 v51, v51
	v_rcp_f32_e32 v52, v52
	s_nop 0
	v_mul_f32_e32 v51, v116, v51
	v_mul_f32_e32 v52, v117, v52
	ds_write_b32 v40, v51 offset:32768
	ds_write_b32 v40, v52 offset:34816
	v_mul_f32_e32 v51, 0xbfb8aa3b, v118
	v_mul_f32_e32 v52, 0xbfb8aa3b, v119
	v_exp_f32_e32 v51, v51
	v_exp_f32_e32 v52, v52
	s_nop 0
	v_add_f32_e32 v51, 1.0, v51
	v_add_f32_e32 v52, 1.0, v52
	v_rcp_f32_e32 v51, v51
	v_rcp_f32_e32 v52, v52
	s_nop 0
	v_mul_f32_e32 v51, v118, v51
	v_mul_f32_e32 v52, v119, v52
	ds_write_b32 v40, v51 offset:36864
	ds_write_b32 v40, v52 offset:38912
	v_mul_f32_e32 v51, 0xbfb8aa3b, v120
	v_mul_f32_e32 v52, 0xbfb8aa3b, v121
	v_exp_f32_e32 v51, v51
	v_exp_f32_e32 v52, v52
	s_nop 0
	v_add_f32_e32 v51, 1.0, v51
	v_add_f32_e32 v52, 1.0, v52
	v_rcp_f32_e32 v51, v51
	v_rcp_f32_e32 v52, v52
	s_nop 0
	v_mul_f32_e32 v51, v120, v51
	v_mul_f32_e32 v52, v121, v52
	ds_write_b32 v40, v51 offset:40960
	ds_write_b32 v40, v52 offset:43008
	v_mul_f32_e32 v51, 0xbfb8aa3b, v122
	v_mul_f32_e32 v52, 0xbfb8aa3b, v123
	v_exp_f32_e32 v51, v51
	v_exp_f32_e32 v52, v52
	s_nop 0
	v_add_f32_e32 v51, 1.0, v51
	v_add_f32_e32 v52, 1.0, v52
	v_rcp_f32_e32 v51, v51
	v_rcp_f32_e32 v52, v52
	s_nop 0
	v_mul_f32_e32 v51, v122, v51
	v_mul_f32_e32 v52, v123, v52
	ds_write_b32 v40, v51 offset:45056
	ds_write_b32 v40, v52 offset:47104
	v_mul_f32_e32 v51, 0xbfb8aa3b, v124
	v_mul_f32_e32 v52, 0xbfb8aa3b, v125
	v_exp_f32_e32 v51, v51
	v_exp_f32_e32 v52, v52
	s_nop 0
	v_add_f32_e32 v51, 1.0, v51
	v_add_f32_e32 v52, 1.0, v52
	v_rcp_f32_e32 v51, v51
	v_rcp_f32_e32 v52, v52
	s_nop 0
	v_mul_f32_e32 v51, v124, v51
	v_mul_f32_e32 v52, v125, v52
	ds_write_b32 v40, v51 offset:49152
	ds_write_b32 v40, v52 offset:51200
	v_mul_f32_e32 v51, 0xbfb8aa3b, v126
	v_mul_f32_e32 v52, 0xbfb8aa3b, v127
	v_exp_f32_e32 v51, v51
	v_exp_f32_e32 v52, v52
	s_nop 0
	v_add_f32_e32 v51, 1.0, v51
	v_add_f32_e32 v52, 1.0, v52
	v_rcp_f32_e32 v51, v51
	v_rcp_f32_e32 v52, v52
	s_nop 0
	v_mul_f32_e32 v51, v126, v51
	v_mul_f32_e32 v52, v127, v52
	ds_write_b32 v40, v51 offset:53248
	ds_write_b32 v40, v52 offset:55296
	v_mul_f32_e32 v51, 0xbfb8aa3b, v128
	v_mul_f32_e32 v52, 0xbfb8aa3b, v129
	v_exp_f32_e32 v51, v51
	v_exp_f32_e32 v52, v52
	s_nop 0
	v_add_f32_e32 v51, 1.0, v51
	v_add_f32_e32 v52, 1.0, v52
	v_rcp_f32_e32 v51, v51
	v_rcp_f32_e32 v52, v52
	s_nop 0
	v_mul_f32_e32 v51, v128, v51
	v_mul_f32_e32 v52, v129, v52
	ds_write_b32 v40, v51 offset:57344
	ds_write_b32 v40, v52 offset:59392
	v_mul_f32_e32 v51, 0xbfb8aa3b, v130
	v_mul_f32_e32 v52, 0xbfb8aa3b, v131
	v_exp_f32_e32 v51, v51
	v_exp_f32_e32 v52, v52
	s_nop 0
	v_add_f32_e32 v51, 1.0, v51
	v_add_f32_e32 v52, 1.0, v52
	v_rcp_f32_e32 v51, v51
	v_rcp_f32_e32 v52, v52
	s_nop 0
	v_mul_f32_e32 v51, v130, v51
	v_mul_f32_e32 v52, v131, v52
	ds_write_b32 v40, v51 offset:61440
	ds_write_b32 v40, v52 offset:63488
	v_mul_f32_e32 v51, 0xbfb8aa3b, v132
	v_mul_f32_e32 v52, 0xbfb8aa3b, v133
	v_exp_f32_e32 v51, v51
	v_exp_f32_e32 v52, v52
	s_nop 0
	v_add_f32_e32 v51, 1.0, v51
	v_add_f32_e32 v52, 1.0, v52
	v_rcp_f32_e32 v51, v51
	v_rcp_f32_e32 v52, v52
	s_nop 0
	v_mul_f32_e32 v51, v132, v51
	v_mul_f32_e32 v52, v133, v52
	ds_write_b32 v50, v51
	ds_write_b32 v50, v52 offset:2048
	v_ashrrev_i32_e32 v9, 31, v8
	v_mov_b32_e32 v12, 0
	v_lshl_add_u64 v[10:11], v[8:9], 2, v[6:7]
	s_mov_b32 s14, 0
	v_mov_b32_e32 v13, v12
	v_mov_b32_e32 v14, v12
	v_mov_b32_e32 v15, v12
	v_mov_b32_e32 v16, v12
	v_mov_b32_e32 v17, v12
	v_mov_b32_e32 v20, v12
	v_mov_b32_e32 v21, v12
	v_mov_b32_e32 v18, v12
	v_mov_b32_e32 v19, v12
	v_mov_b32_e32 v22, v12
	v_mov_b32_e32 v23, v12
	v_mov_b32_e32 v24, v12
	v_mov_b32_e32 v25, v12
	v_mov_b32_e32 v26, v12
	v_mov_b32_e32 v27, v12
	v_mov_b32_e32 v9, v12
	s_waitcnt lgkmcnt(0)
	s_barrier
